# v16 plus K-loop MMA(1,0)+MMA(1,1) segments fused: 12 instead of 16 barriers per iteration, P4 and P8 DMA issue hoisted one segment
# speedup vs baseline: 1.0049x; 1.0049x over previous
; #define PG8_STAGE(bufoff, gbase, voff) do { _Pragma("unroll") for (int _i = 0; _i < 2; ++_i) \
;         __builtin_amdgcn_global_load_lds((const unsigned*)((const char*)(gbase) + (voff)[_i]), (LAS unsigned*)(lds + (bufoff) + ldsw + _i * 8192), 16, 0, 0); } while (0)
; #define PG8_LDA(dst, b, h) do { _Pragma("unroll") for (int m = 0; m < 4; ++m) _Pragma("unroll") for (int k = 0; k < 2; ++k) dst[m][k] = *(const LAS bf16x8*)(lds + PG8_SA(b, h) + aoff + m * 2048 + k * 1024); } while (0)
; #define PG8_LDB(dst, b, h) do { _Pragma("unroll") for (int n = 0; n < 2; ++n) _Pragma("unroll") for (int k = 0; k < 2; ++k) dst[n][k] = *(const LAS bf16x8*)(lds + PG8_SB(b, h) + boff + n * 2048 + k * 1024); } while (0)
; #define PG8_MMA(ai, bj, At, Bt) do { __builtin_amdgcn_s_setprio(1); _Pragma("unroll") for (int m = 0; m < 4; ++m) _Pragma("unroll") for (int n = 0; n < 2; ++n) _Pragma("unroll") for (int k = 0; k < 2; ++k) \
;         acc[ai][bj][m][n] = __builtin_amdgcn_mfma_f32_16x16x32_bf16(Bt[n][k], At[m][k], acc[ai][bj][m][n], 0, 0, 0); __builtin_amdgcn_s_setprio(0); } while (0)
; #define PG8_WAIT_V(n) asm volatile("s_waitcnt vmcnt(" #n ")" ::: "memory")
; #define PG8_WAIT_L(n) asm volatile("s_waitcnt lgkmcnt(" #n ")" ::: "memory")
; template <class Epi>
; __device__ __forceinline__ void gemm_phase(LAS unsigned char* lds, const Gemm g, const StaticOrder& S, const Epi& E, const int tidx) {
;     ...
;         for (int t = 0; t < nt; t += 2) {
;             const bool last = (t == nt - 2);
;             const char* a1 = cA + (size_t)(t + 1) * kstep;
;             const char* a2 = last ? nA : cA + (size_t)(t + 2) * kstep; const char* b2 = last ? nB : cB + (size_t)(t + 2) * kstep;
;             const char* a3 = a2 + kstep; const char* b3 = b2 + kstep;
;             PG8_LDB(B0, 0, 0); PG8_SCHED; PG8_LDA(At, 0, 0); PG8_STAGE(PG8_SA(1, 1), a1 + hstep, voffA);
;             PG8_WAIT_L(8); PG8_BAR; PG8_WAIT_L(0); PG8_MMA(0, 0, At, B0); PG8_BAR; PG8_SCHED;
;             PG8_LDB(B1, 0, 1); PG8_STAGE(PG8_SB(0, 0), b2, voffB);
;             PG8_BAR; PG8_WAIT_L(0); PG8_MMA(0, 1, At, B1); PG8_BAR;
;             PG8_LDA(At, 0, 1); PG8_STAGE(PG8_SA(0, 0), a2, voffA);
;             PG8_BAR; PG8_WAIT_L(0); PG8_MMA(1, 0, At, B0); PG8_BAR; PG8_SCHED;
;             PG8_STAGE(PG8_SB(0, 1), b2 + hstep, voffB);
;             PG8_WAIT_V(6); PG8_BAR; PG8_MMA(1, 1, At, B1); PG8_BAR;
.LBB0_713:
	s_add_i32 s8, s4, 2
	s_add_u32 s6, s2, 0x80
	s_addc_u32 s5, s3, 0
	s_add_i32 s9, 0, 0x10000
	v_add_u32_e32 v140, s9, v243
	s_waitcnt lgkmcnt(0)
	ds_read_b128 v[128:131], v140
	ds_read_b128 v[132:135], v140 offset:1024
	ds_read_b128 v[136:139], v140 offset:2048
	ds_read_b128 v[140:143], v140 offset:3072
	s_cmp_eq_u32 s59, s4
	s_cselect_b32 s4, s90, s6
	s_cselect_b32 s5, s91, s5
	s_cselect_b32 s7, s93, s1
	s_cselect_b32 s6, s92, s0
	v_lshl_add_u64 v[176:177], s[2:3], 0, v[206:207]
	s_add_i32 m0, s31, 0xc000
	ds_read_b128 v[144:147], v240
	ds_read_b128 v[148:151], v240 offset:1024
	ds_read_b128 v[152:155], v240 offset:2048
	ds_read_b128 v[156:159], v240 offset:3072
	ds_read_b128 v[160:163], v240 offset:4096
	ds_read_b128 v[164:167], v240 offset:5120
	ds_read_b128 v[168:171], v240 offset:6144
	ds_read_b128 v[172:175], v240 offset:7168
	global_load_lds_dwordx4 v[176:177], off
	v_lshl_add_u64 v[176:177], s[2:3], 0, v[208:209]
	s_add_i32 m0, s31, 0xe000
	s_nop 0
	global_load_lds_dwordx4 v[176:177], off
	s_waitcnt lgkmcnt(8)
	s_barrier
	s_waitcnt lgkmcnt(0)
	s_setprio 1
	s_waitcnt lgkmcnt(0)
	v_mfma_f32_16x16x32_bf16 v[116:119], v[128:131], v[144:147], v[116:119]
	v_mfma_f32_16x16x32_bf16 v[112:115], v[136:139], v[144:147], v[112:115]
	v_mfma_f32_16x16x32_bf16 v[100:103], v[128:131], v[152:155], v[100:103]
	v_mfma_f32_16x16x32_bf16 v[96:99], v[136:139], v[152:155], v[96:99]
	v_mfma_f32_16x16x32_bf16 v[84:87], v[128:131], v[160:163], v[84:87]
	v_mfma_f32_16x16x32_bf16 v[80:83], v[136:139], v[160:163], v[80:83]
	v_mfma_f32_16x16x32_bf16 v[68:71], v[128:131], v[168:171], v[68:71]
	v_mfma_f32_16x16x32_bf16 v[64:67], v[136:139], v[168:171], v[64:67]
	v_mfma_f32_16x16x32_bf16 v[116:119], v[132:135], v[148:151], v[116:119]
	v_mfma_f32_16x16x32_bf16 v[112:115], v[140:143], v[148:151], v[112:115]
	v_mfma_f32_16x16x32_bf16 v[100:103], v[132:135], v[156:159], v[100:103]
	v_mfma_f32_16x16x32_bf16 v[96:99], v[140:143], v[156:159], v[96:99]
	v_mfma_f32_16x16x32_bf16 v[84:87], v[132:135], v[164:167], v[84:87]
	v_mfma_f32_16x16x32_bf16 v[80:83], v[140:143], v[164:167], v[80:83]
	v_mfma_f32_16x16x32_bf16 v[68:71], v[132:135], v[172:175], v[68:71]
	v_mfma_f32_16x16x32_bf16 v[64:67], v[140:143], v[172:175], v[64:67]
	s_setprio 0
	s_barrier
	s_add_i32 s10, 0, 0x14000
	s_add_i32 s9, s9, s30
	v_add_u32_e32 v188, s10, v243
	v_lshl_add_u64 v[212:213], s[6:7], 0, v[202:203]
	s_mov_b32 m0, s9
	ds_read_b128 v[176:179], v188
	ds_read_b128 v[180:183], v188 offset:1024
	ds_read_b128 v[184:187], v188 offset:2048
	ds_read_b128 v[188:191], v188 offset:3072
	global_load_lds_dwordx4 v[212:213], off
	v_lshl_add_u64 v[214:215], s[6:7], 0, v[198:199]
	s_add_i32 m0, s9, 0x2000
	s_nop 0
	global_load_lds_dwordx4 v[214:215], off
	s_barrier
	s_waitcnt lgkmcnt(0)
	s_setprio 1
	s_waitcnt lgkmcnt(0)
	v_mfma_f32_16x16x32_bf16 v[124:127], v[176:179], v[144:147], v[124:127]
	v_mfma_f32_16x16x32_bf16 v[120:123], v[184:187], v[144:147], v[120:123]
	v_mfma_f32_16x16x32_bf16 v[108:111], v[176:179], v[152:155], v[108:111]
	v_mfma_f32_16x16x32_bf16 v[104:107], v[184:187], v[152:155], v[104:107]
	v_mfma_f32_16x16x32_bf16 v[92:95], v[176:179], v[160:163], v[92:95]
	v_mfma_f32_16x16x32_bf16 v[88:91], v[184:187], v[160:163], v[88:91]
	v_mfma_f32_16x16x32_bf16 v[76:79], v[176:179], v[168:171], v[76:79]
	v_mfma_f32_16x16x32_bf16 v[72:75], v[184:187], v[168:171], v[72:75]
	v_mfma_f32_16x16x32_bf16 v[124:127], v[180:183], v[148:151], v[124:127]
	v_mfma_f32_16x16x32_bf16 v[120:123], v[188:191], v[148:151], v[120:123]
	v_mfma_f32_16x16x32_bf16 v[108:111], v[180:183], v[156:159], v[108:111]
	v_mfma_f32_16x16x32_bf16 v[104:107], v[188:191], v[156:159], v[104:107]
	v_mfma_f32_16x16x32_bf16 v[92:95], v[180:183], v[164:167], v[92:95]
	v_mfma_f32_16x16x32_bf16 v[88:91], v[188:191], v[164:167], v[88:91]
	v_mfma_f32_16x16x32_bf16 v[76:79], v[180:183], v[172:175], v[76:79]
	v_mfma_f32_16x16x32_bf16 v[72:75], v[188:191], v[172:175], v[72:75]
	s_setprio 0
	s_mov_b32 m0, s31
	v_lshl_add_u64 v[216:217], s[4:5], 0, v[200:201]
	s_barrier
	ds_read_b128 v[144:147], v240 offset:16384
	ds_read_b128 v[148:151], v240 offset:17408
	ds_read_b128 v[152:155], v240 offset:18432
	ds_read_b128 v[156:159], v240 offset:19456
	ds_read_b128 v[160:163], v240 offset:20480
	ds_read_b128 v[164:167], v240 offset:21504
	ds_read_b128 v[168:171], v240 offset:22528
	ds_read_b128 v[172:175], v240 offset:23552
	global_load_lds_dwordx4 v[216:217], off
	v_lshl_add_u64 v[218:219], s[4:5], 0, v[196:197]
	s_mov_b32 m0, s34
	s_nop 0
	global_load_lds_dwordx4 v[218:219], off
	s_add_u32 s6, s6, s14
	s_addc_u32 s7, s7, 0
	s_add_i32 s9, s10, s30
	v_lshl_add_u64 v[220:221], s[6:7], 0, v[202:203]
	s_mov_b32 m0, s9
	v_lshl_add_u64 v[222:223], s[6:7], 0, v[198:199]
	global_load_lds_dwordx4 v[220:221], off
	s_add_i32 m0, s9, 0x2000
	s_nop 0
	global_load_lds_dwordx4 v[222:223], off
	s_waitcnt vmcnt(6)
	s_barrier
	s_waitcnt lgkmcnt(0)
	s_setprio 1
	s_waitcnt lgkmcnt(0)
	s_cmp_eq_u32 s13, 0x80
	s_cbranch_scc1 .Lskip_mma_2
; #define PG8_STAGE(bufoff, gbase, voff) do { _Pragma("unroll") for (int _i = 0; _i < 2; ++_i) \
;         __builtin_amdgcn_global_load_lds((const unsigned*)((const char*)(gbase) + (voff)[_i]), (LAS unsigned*)(lds + (bufoff) + ldsw + _i * 8192), 16, 0, 0); } while (0)
; #define PG8_LDA(dst, b, h) do { _Pragma("unroll") for (int m = 0; m < 4; ++m) _Pragma("unroll") for (int k = 0; k < 2; ++k) dst[m][k] = *(const LAS bf16x8*)(lds + PG8_SA(b, h) + aoff + m * 2048 + k * 1024); } while (0)
; #define PG8_LDB(dst, b, h) do { _Pragma("unroll") for (int n = 0; n < 2; ++n) _Pragma("unroll") for (int k = 0; k < 2; ++k) dst[n][k] = *(const LAS bf16x8*)(lds + PG8_SB(b, h) + boff + n * 2048 + k * 1024); } while (0)
; #define PG8_MMA(ai, bj, At, Bt) do { __builtin_amdgcn_s_setprio(1); _Pragma("unroll") for (int m = 0; m < 4; ++m) _Pragma("unroll") for (int n = 0; n < 2; ++n) _Pragma("unroll") for (int k = 0; k < 2; ++k) \
;         acc[ai][bj][m][n] = __builtin_amdgcn_mfma_f32_16x16x32_bf16(Bt[n][k], At[m][k], acc[ai][bj][m][n], 0, 0, 0); __builtin_amdgcn_s_setprio(0); } while (0)
; #define PG8_WAIT_V(n) asm volatile("s_waitcnt vmcnt(" #n ")" ::: "memory")
; #define PG8_WAIT_L(n) asm volatile("s_waitcnt lgkmcnt(" #n ")" ::: "memory")
; #define PG8_BAR __builtin_amdgcn_s_barrier()
; #define PG8_SCHED __builtin_amdgcn_sched_barrier(0)
; template <class Epi>
; __device__ __forceinline__ void gemm_phase(LAS unsigned char* lds, const Gemm g, const StaticOrder& S, const Epi& E, const int tidx) {
;     ...
;             PG8_BAR; PG8_WAIT_L(0); PG8_MMA(1, 0, At, B0); PG8_BAR; PG8_SCHED;
;             PG8_STAGE(PG8_SB(0, 1), b2 + hstep, voffB);
;             PG8_WAIT_V(6); PG8_BAR; PG8_MMA(1, 1, At, B1); PG8_BAR;
;             PG8_LDB(B0, 1, 0); PG8_SCHED; PG8_LDA(At, 1, 0); PG8_STAGE(PG8_SA(0, 1), a2 + hstep, voffA);
;             PG8_WAIT_L(8); PG8_BAR; PG8_WAIT_L(0); PG8_MMA(0, 0, At, B0); PG8_BAR; PG8_SCHED;
;             PG8_LDB(B1, 1, 1); PG8_STAGE(PG8_SB(1, 0), b3, voffB);
;             PG8_BAR; PG8_WAIT_L(0); PG8_MMA(0, 1, At, B1); PG8_BAR;
	v_mfma_f32_16x16x32_bf16 v[52:55], v[128:131], v[144:147], v[52:55]
	v_mfma_f32_16x16x32_bf16 v[48:51], v[136:139], v[144:147], v[48:51]
	v_mfma_f32_16x16x32_bf16 v[36:39], v[128:131], v[152:155], v[36:39]
	v_mfma_f32_16x16x32_bf16 v[32:35], v[136:139], v[152:155], v[32:35]
	v_mfma_f32_16x16x32_bf16 v[20:23], v[128:131], v[160:163], v[20:23]
	v_mfma_f32_16x16x32_bf16 v[16:19], v[136:139], v[160:163], v[16:19]
	v_mfma_f32_16x16x32_bf16 v[4:7], v[128:131], v[168:171], v[4:7]
	v_mfma_f32_16x16x32_bf16 v[0:3], v[136:139], v[168:171], v[0:3]
	v_mfma_f32_16x16x32_bf16 v[52:55], v[132:135], v[148:151], v[52:55]
	v_mfma_f32_16x16x32_bf16 v[48:51], v[140:143], v[148:151], v[48:51]
	v_mfma_f32_16x16x32_bf16 v[36:39], v[132:135], v[156:159], v[36:39]
	v_mfma_f32_16x16x32_bf16 v[32:35], v[140:143], v[156:159], v[32:35]
	v_mfma_f32_16x16x32_bf16 v[20:23], v[132:135], v[164:167], v[20:23]
	v_mfma_f32_16x16x32_bf16 v[16:19], v[140:143], v[164:167], v[16:19]
	v_mfma_f32_16x16x32_bf16 v[4:7], v[132:135], v[172:175], v[4:7]
	v_mfma_f32_16x16x32_bf16 v[0:3], v[140:143], v[172:175], v[0:3]
	v_mfma_f32_16x16x32_bf16 v[60:63], v[176:179], v[144:147], v[60:63]
	v_mfma_f32_16x16x32_bf16 v[56:59], v[184:187], v[144:147], v[56:59]
	v_mfma_f32_16x16x32_bf16 v[44:47], v[176:179], v[152:155], v[44:47]
	v_mfma_f32_16x16x32_bf16 v[40:43], v[184:187], v[152:155], v[40:43]
	v_mfma_f32_16x16x32_bf16 v[28:31], v[176:179], v[160:163], v[28:31]
	v_mfma_f32_16x16x32_bf16 v[24:27], v[184:187], v[160:163], v[24:27]
	v_mfma_f32_16x16x32_bf16 v[12:15], v[176:179], v[168:171], v[12:15]
	v_mfma_f32_16x16x32_bf16 v[8:11], v[184:187], v[168:171], v[8:11]
	v_mfma_f32_16x16x32_bf16 v[60:63], v[180:183], v[148:151], v[60:63]
	v_mfma_f32_16x16x32_bf16 v[56:59], v[188:191], v[148:151], v[56:59]
	v_mfma_f32_16x16x32_bf16 v[44:47], v[180:183], v[156:159], v[44:47]
	v_mfma_f32_16x16x32_bf16 v[40:43], v[188:191], v[156:159], v[40:43]
	v_mfma_f32_16x16x32_bf16 v[28:31], v[180:183], v[164:167], v[28:31]
	v_mfma_f32_16x16x32_bf16 v[24:27], v[188:191], v[164:167], v[24:27]
	v_mfma_f32_16x16x32_bf16 v[12:15], v[180:183], v[172:175], v[12:15]
	v_mfma_f32_16x16x32_bf16 v[8:11], v[188:191], v[172:175], v[8:11]
.Lskip_mma_2:
.Lskip_mma_3:
	s_setprio 0
	s_add_i32 s6, 0, 0x18000
	v_add_u32_e32 v140, s6, v243
	s_barrier
	ds_read_b128 v[128:131], v140
	ds_read_b128 v[132:135], v140 offset:1024
	ds_read_b128 v[136:139], v140 offset:2048
	ds_read_b128 v[140:143], v140 offset:3072
	s_add_u32 s4, s4, s14
	s_addc_u32 s5, s5, 0
	s_mov_b32 m0, s35
	v_lshl_add_u64 v[176:177], s[4:5], 0, v[200:201]
	ds_read_b128 v[144:147], v240 offset:32768
	ds_read_b128 v[148:151], v240 offset:33792
	ds_read_b128 v[152:155], v240 offset:34816
	ds_read_b128 v[156:159], v240 offset:35840
	ds_read_b128 v[160:163], v240 offset:36864
	ds_read_b128 v[164:167], v240 offset:37888
	ds_read_b128 v[168:171], v240 offset:38912
	ds_read_b128 v[172:175], v240 offset:39936
	global_load_lds_dwordx4 v[176:177], off
	v_lshl_add_u64 v[176:177], s[4:5], 0, v[196:197]
	s_mov_b32 m0, s54
	s_nop 0
	global_load_lds_dwordx4 v[176:177], off
	s_waitcnt lgkmcnt(8)
	s_barrier
	s_waitcnt lgkmcnt(0)
	s_setprio 1
	s_waitcnt lgkmcnt(0)
	v_mfma_f32_16x16x32_bf16 v[116:119], v[128:131], v[144:147], v[116:119]
	v_mfma_f32_16x16x32_bf16 v[112:115], v[136:139], v[144:147], v[112:115]
	v_mfma_f32_16x16x32_bf16 v[100:103], v[128:131], v[152:155], v[100:103]
	v_mfma_f32_16x16x32_bf16 v[96:99], v[136:139], v[152:155], v[96:99]
	v_mfma_f32_16x16x32_bf16 v[84:87], v[128:131], v[160:163], v[84:87]
	v_mfma_f32_16x16x32_bf16 v[80:83], v[136:139], v[160:163], v[80:83]
	v_mfma_f32_16x16x32_bf16 v[68:71], v[128:131], v[168:171], v[68:71]
	v_mfma_f32_16x16x32_bf16 v[64:67], v[136:139], v[168:171], v[64:67]
	v_mfma_f32_16x16x32_bf16 v[116:119], v[132:135], v[148:151], v[116:119]
	v_mfma_f32_16x16x32_bf16 v[112:115], v[140:143], v[148:151], v[112:115]
	v_mfma_f32_16x16x32_bf16 v[100:103], v[132:135], v[156:159], v[100:103]
	v_mfma_f32_16x16x32_bf16 v[96:99], v[140:143], v[156:159], v[96:99]
	v_mfma_f32_16x16x32_bf16 v[84:87], v[132:135], v[164:167], v[84:87]
	v_mfma_f32_16x16x32_bf16 v[80:83], v[140:143], v[164:167], v[80:83]
	v_mfma_f32_16x16x32_bf16 v[68:71], v[132:135], v[172:175], v[68:71]
	v_mfma_f32_16x16x32_bf16 v[64:67], v[140:143], v[172:175], v[64:67]
	s_setprio 0
	s_barrier
	s_add_i32 s4, 0, 0x1c000
	s_add_i32 s5, s6, s30
	v_add_u32_e32 v188, s4, v243
	v_lshl_add_u64 v[212:213], v[212:213], 0, s[16:17]
	s_mov_b32 m0, s5
	ds_read_b128 v[176:179], v188
	ds_read_b128 v[180:183], v188 offset:1024
	ds_read_b128 v[184:187], v188 offset:2048
	ds_read_b128 v[188:191], v188 offset:3072
	global_load_lds_dwordx4 v[212:213], off
	v_lshl_add_u64 v[212:213], v[214:215], 0, s[16:17]
	s_add_i32 m0, s5, 0x2000
	s_nop 0
	global_load_lds_dwordx4 v[212:213], off
	s_barrier
; #define INP(i) (*(const float* const __attribute__((address_space(4)))*)(ka_base() + 8 * (i)))
; #define OUTP() (*(float* const __attribute__((address_space(4)))*)(ka_base() + 8 * 21))
; #define WSP() (*(unsigned char* const __attribute__((address_space(4)))*)(ka_base() + 8 * 22))
; #define PG8_STAGE(bufoff, gbase, voff) do { _Pragma("unroll") for (int _i = 0; _i < 2; ++_i) \
;         __builtin_amdgcn_global_load_lds((const unsigned*)((const char*)(gbase) + (voff)[_i]), (LAS unsigned*)(lds + (bufoff) + ldsw + _i * 8192), 16, 0, 0); } while (0)
; #define PG8_LDA(dst, b, h) do { _Pragma("unroll") for (int m = 0; m < 4; ++m) _Pragma("unroll") for (int k = 0; k < 2; ++k) dst[m][k] = *(const LAS bf16x8*)(lds + PG8_SA(b, h) + aoff + m * 2048 + k * 1024); } while (0)
; #define PG8_WAIT_V(n) asm volatile("s_waitcnt vmcnt(" #n ")" ::: "memory")
; #define PG8_WAIT_L(n) asm volatile("s_waitcnt lgkmcnt(" #n ")" ::: "memory")
; #define PG8_BAR __builtin_amdgcn_s_barrier()
; #define PG8_SCHED __builtin_amdgcn_sched_barrier(0)
; template <class Epi>
; __device__ __forceinline__ void gemm_phase(LAS unsigned char* lds, const Gemm g, const StaticOrder& S, const Epi& E, const int tidx) {
;     ...
;             PG8_BAR; PG8_WAIT_L(0); PG8_MMA(0, 1, At, B1); PG8_BAR;
;             PG8_LDA(At, 1, 1); PG8_STAGE(PG8_SA(1, 0), a3, voffA);
;             PG8_BAR; PG8_WAIT_L(0); PG8_MMA(1, 0, At, B0); PG8_BAR; PG8_SCHED;
;             PG8_STAGE(PG8_SB(1, 1), b3 + hstep, voffB);
;             PG8_WAIT_V(6); PG8_BAR; PG8_MMA(1, 1, At, B1); PG8_BAR;
;         }
;         E(acc, cur, wr, wc, fr, fq);
;     __device__ __forceinline__ void res(const f32x4 (&acc)[2][2][4][2], const pg8::Unit& u, int wr, int wc, int fr, int fq) const {
;         float* out = OUTP(); bf16_t* xb = (bf16_t*)(WSP() + WS_XB);
;         const int row0 = u.pm * 256 + wr * 64 + fr, col0 = u.pn * 256 + wc * 32 + 4 * fq;
; #pragma unroll
;         for (int ai = 0; ai < 2; ++ai) {
;             f32x4 xin[4][2][2];
; #pragma unroll
;             for (int m = 0; m < 4; ++m) {
;                 const int r = row0 + ai * 128 + m * 16;
;                 const bool ok = row_valid(g, r);
;                 const int rq = ok ? r : 0;
;                 const float* yp = (first ? (rq < 32768 ? INP(0) + ((size_t)g * 32768 + rq) * 1024 : INP(1) + (size_t)(rq - 32768) * 1024) : (const float*)yrow(out, g, rq)) + col0;
	s_waitcnt lgkmcnt(0)
	s_setprio 1
	s_waitcnt lgkmcnt(0)
	v_mfma_f32_16x16x32_bf16 v[124:127], v[176:179], v[144:147], v[124:127]
	v_mfma_f32_16x16x32_bf16 v[120:123], v[184:187], v[144:147], v[120:123]
	v_mfma_f32_16x16x32_bf16 v[108:111], v[176:179], v[152:155], v[108:111]
	v_mfma_f32_16x16x32_bf16 v[104:107], v[184:187], v[152:155], v[104:107]
	v_mfma_f32_16x16x32_bf16 v[92:95], v[176:179], v[160:163], v[92:95]
	v_mfma_f32_16x16x32_bf16 v[88:91], v[184:187], v[160:163], v[88:91]
	v_mfma_f32_16x16x32_bf16 v[76:79], v[176:179], v[168:171], v[76:79]
	v_mfma_f32_16x16x32_bf16 v[72:75], v[184:187], v[168:171], v[72:75]
	v_mfma_f32_16x16x32_bf16 v[124:127], v[180:183], v[148:151], v[124:127]
	v_mfma_f32_16x16x32_bf16 v[120:123], v[188:191], v[148:151], v[120:123]
	v_mfma_f32_16x16x32_bf16 v[108:111], v[180:183], v[156:159], v[108:111]
	v_mfma_f32_16x16x32_bf16 v[104:107], v[188:191], v[156:159], v[104:107]
	v_mfma_f32_16x16x32_bf16 v[92:95], v[180:183], v[164:167], v[92:95]
	v_mfma_f32_16x16x32_bf16 v[88:91], v[188:191], v[164:167], v[88:91]
	v_mfma_f32_16x16x32_bf16 v[76:79], v[180:183], v[172:175], v[76:79]
	v_mfma_f32_16x16x32_bf16 v[72:75], v[188:191], v[172:175], v[72:75]
	s_setprio 0
	s_mov_b32 m0, s57
	v_lshl_add_u64 v[212:213], v[216:217], 0, s[16:17]
	s_barrier
	ds_read_b128 v[144:147], v240 offset:49152
	ds_read_b128 v[148:151], v240 offset:50176
	ds_read_b128 v[152:155], v240 offset:51200
	ds_read_b128 v[156:159], v240 offset:52224
	ds_read_b128 v[160:163], v240 offset:53248
	ds_read_b128 v[164:167], v240 offset:54272
	ds_read_b128 v[168:171], v240 offset:55296
	ds_read_b128 v[172:175], v240 offset:56320
	global_load_lds_dwordx4 v[212:213], off
	v_lshl_add_u64 v[212:213], v[218:219], 0, s[16:17]
	s_mov_b32 m0, s58
	s_nop 0
	global_load_lds_dwordx4 v[212:213], off
	s_add_i32 s4, s4, s30
	v_lshl_add_u64 v[212:213], v[220:221], 0, s[16:17]
	s_mov_b32 m0, s4
	s_nop 0
	global_load_lds_dwordx4 v[212:213], off
	v_lshl_add_u64 v[212:213], v[222:223], 0, s[16:17]
	s_add_i32 m0, s4, 0x2000
	s_nop 0
	global_load_lds_dwordx4 v[212:213], off
	s_waitcnt vmcnt(6)
	s_barrier
	s_waitcnt lgkmcnt(0)
	s_setprio 1
	s_waitcnt lgkmcnt(0)
	s_cmp_eq_u32 s13, 0x80
	s_cbranch_scc1 .Lskip_mma_6
	v_mfma_f32_16x16x32_bf16 v[52:55], v[128:131], v[144:147], v[52:55]
	v_mfma_f32_16x16x32_bf16 v[48:51], v[136:139], v[144:147], v[48:51]
	v_mfma_f32_16x16x32_bf16 v[36:39], v[128:131], v[152:155], v[36:39]
	v_mfma_f32_16x16x32_bf16 v[32:35], v[136:139], v[152:155], v[32:35]
	v_mfma_f32_16x16x32_bf16 v[20:23], v[128:131], v[160:163], v[20:23]
	v_mfma_f32_16x16x32_bf16 v[16:19], v[136:139], v[160:163], v[16:19]
	v_mfma_f32_16x16x32_bf16 v[4:7], v[128:131], v[168:171], v[4:7]
	v_mfma_f32_16x16x32_bf16 v[0:3], v[136:139], v[168:171], v[0:3]
	v_mfma_f32_16x16x32_bf16 v[52:55], v[132:135], v[148:151], v[52:55]
	v_mfma_f32_16x16x32_bf16 v[48:51], v[140:143], v[148:151], v[48:51]
	v_mfma_f32_16x16x32_bf16 v[36:39], v[132:135], v[156:159], v[36:39]
	v_mfma_f32_16x16x32_bf16 v[32:35], v[140:143], v[156:159], v[32:35]
	v_mfma_f32_16x16x32_bf16 v[20:23], v[132:135], v[164:167], v[20:23]
	v_mfma_f32_16x16x32_bf16 v[16:19], v[140:143], v[164:167], v[16:19]
	v_mfma_f32_16x16x32_bf16 v[4:7], v[132:135], v[172:175], v[4:7]
	v_mfma_f32_16x16x32_bf16 v[0:3], v[140:143], v[172:175], v[0:3]
	v_mfma_f32_16x16x32_bf16 v[60:63], v[176:179], v[144:147], v[60:63]
	v_mfma_f32_16x16x32_bf16 v[56:59], v[184:187], v[144:147], v[56:59]
	v_mfma_f32_16x16x32_bf16 v[44:47], v[176:179], v[152:155], v[44:47]
	v_mfma_f32_16x16x32_bf16 v[40:43], v[184:187], v[152:155], v[40:43]
	v_mfma_f32_16x16x32_bf16 v[28:31], v[176:179], v[160:163], v[28:31]
	v_mfma_f32_16x16x32_bf16 v[24:27], v[184:187], v[160:163], v[24:27]
	v_mfma_f32_16x16x32_bf16 v[12:15], v[176:179], v[168:171], v[12:15]
	v_mfma_f32_16x16x32_bf16 v[8:11], v[184:187], v[168:171], v[8:11]
	v_mfma_f32_16x16x32_bf16 v[60:63], v[180:183], v[148:151], v[60:63]
	v_mfma_f32_16x16x32_bf16 v[56:59], v[188:191], v[148:151], v[56:59]
	v_mfma_f32_16x16x32_bf16 v[44:47], v[180:183], v[156:159], v[44:47]
	v_mfma_f32_16x16x32_bf16 v[40:43], v[188:191], v[156:159], v[40:43]
	v_mfma_f32_16x16x32_bf16 v[28:31], v[180:183], v[164:167], v[28:31]
	v_mfma_f32_16x16x32_bf16 v[24:27], v[188:191], v[164:167], v[24:27]
	v_mfma_f32_16x16x32_bf16 v[12:15], v[180:183], v[172:175], v[12:15]
	v_mfma_f32_16x16x32_bf16 v[8:11], v[188:191], v[172:175], v[8:11]
.Lskip_mma_6:
.Lskip_mma_7:
	s_setprio 0
	s_add_u32 s2, s2, 0x100
	s_addc_u32 s3, s3, 0
	s_add_u32 s0, s0, 0x100
	s_addc_u32 s1, s1, 0
	s_cmp_ge_u32 s8, s55
	s_mov_b32 s4, s8
	s_barrier
	s_cbranch_scc0 .LBB0_713
	s_mov_b64 s[0:1], -1
	s_mov_b64 s[94:95], 0
	s_cmp_lt_i32 s26, 3
	s_mov_b64 s[2:3], 0
	s_cbranch_scc1 .LBB0_789
	s_cmp_gt_i32 s26, 3
	s_cbranch_scc0 .LBB0_994
	s_cmp_eq_u32 s26, 4
	s_mov_b64 s[2:3], -1
	s_cbranch_scc0 .LBB0_993
	v_readlane_b32 s6, v254, 34
	v_readlane_b32 s7, v254, 35
	s_mov_b64 s[0:1], s[6:7]
	s_load_dwordx2 s[96:97], s[0:1], 0xa8
	v_lshl_add_u32 v214, s13, 8, v239
	v_readlane_b32 s0, v254, 39
	s_mov_b32 s10, 0x8000
	v_cmp_gt_i32_e32 vcc, s61, v214
	v_readlane_b32 s1, v254, 40
	v_cmp_gt_i32_e64 s[2:3], s10, v214
	s_and_b64 s[0:1], s[0:1], vcc
	s_or_b64 s[8:9], s[2:3], s[0:1]
	v_cndmask_b32_e64 v128, 0, v214, s[8:9]
	s_movk_i32 s0, 0x7fff
	v_add_u32_e32 v192, 0xffff8000, v128
	v_ashrrev_i32_e32 v129, 31, v128
	v_cmp_gt_i32_e64 s[44:45], s10, v128
	v_cmp_lt_i32_e64 s[4:5], s0, v128
	s_mov_b64 s[0:1], -1
	s_and_b64 vcc, exec, s[78:79]
	v_cndmask_b32_e64 v219, 0, v129, s[44:45]
	v_cndmask_b32_e64 v218, v192, v128, s[44:45]
	s_cbranch_vccz .LBB0_719
	v_mov_b32_e32 v130, s81
	v_cndmask_b32_e64 v130, v248, v130, s[44:45]
	v_mov_b32_e32 v131, v193
	s_waitcnt lgkmcnt(0)
	v_lshl_add_u64 v[132:133], s[96:97], 0, v[130:131]
	s_mov_b64 s[0:1], 0
	v_mov_b64_e32 v[130:131], v[218:219]
